# v62 + P6 EpiAct ACT stores written through (sc1), all rounds
# baseline (speedup 1.0000x reference)
; __device__ __forceinline__ unsigned cvt_pk_bf16(float lo, float hi) { unsigned r; asm volatile("v_cvt_pk_bf16_f32 %0, %1, %2" : "=v"(r) : "v"(lo), "v"(hi)); return r; }
; #define LAS __attribute__((address_space(3)))
; __device__ __forceinline__ float siluf_(float x) { return x * __builtin_amdgcn_rcpf(1.0f + __builtin_amdgcn_exp2f(-1.4426950408889634f * x)); }
; __device__ __forceinline__ float rstd_of(float ss) { return __builtin_amdgcn_rsqf(ss * (1.0f / DM) + EPS); }
;     __device__ __forceinline__ void operator()(const pg8::f32x4 (&acc)[2][2][4][2], const Unit& u, int wr, int wc, int fr, int fq) const {
;         const int row0 = u.pm * BM + wr * 64, lane = fr + 16 * fq, rr = lane >> 2, sl = lane & 3;
;         LAS unsigned char* W = scr + (wr * 4 + wc) * 2048;
;         bf16* outp = ACT + (size_t)(row0 + rr) * DFF + u.pn * HALF + wc * 32 + sl * 8;
; #pragma unroll
;         for (int ai = 0; ai < 2; ++ai)
; #pragma unroll
;             for (int m = 0; m < 4; ++m) { const int rg = ai * HALF + m * 16; const float rs = rstd_of(SS1[row0 + rg + fr]);
;                 const pg8::f32x4 g0 = acc[ai][0][m][0] * rs, g1 = acc[ai][0][m][1] * rs, u0 = acc[ai][1][m][0] * rs, u1 = acc[ai][1][m][1] * rs;
;                 u32x4 w; w.x = cvt_pk_bf16(siluf_(g0[0]) * u0[0], siluf_(g0[1]) * u0[1]); w.y = cvt_pk_bf16(siluf_(g0[2]) * u0[2], siluf_(g0[3]) * u0[3]);
;                 w.z = cvt_pk_bf16(siluf_(g1[0]) * u1[0], siluf_(g1[1]) * u1[1]); w.w = cvt_pk_bf16(siluf_(g1[2]) * u1[2], siluf_(g1[3]) * u1[3]);
;                 *(LAS u32x4*)epi_slot(W, fr, fq + 4 * (m & 1)) = w;
;                 const u32x4 o = *(const LAS u32x4*)epi_slot(W, rr, sl + 4 * (m & 1));
;                 *(u32x4*)(outp + (size_t)rg * DFF) = o; }
.LBB0_880:
	s_lshl_b32 s4, s4, 8
	s_add_i32 s21, s4, s42
	v_or_b32_e32 v148, s21, v152
	v_ashrrev_i32_e32 v149, 31, v148
	v_lshl_add_u64 v[150:151], v[148:149], 2, s[14:15]
	v_lshlrev_b32_e32 v208, 2, v152
	v_add_u32_e32 v209, 64, v208
	v_add_u32_e32 v210, 0x80, v208
	v_add_u32_e32 v211, 0xc0, v208
	ds_bpermute_b32 v200, v208, v234
	ds_bpermute_b32 v201, v209, v234
	ds_bpermute_b32 v202, v210, v234
	ds_bpermute_b32 v203, v211, v234
	ds_bpermute_b32 v204, v208, v235
	ds_bpermute_b32 v205, v209, v235
	ds_bpermute_b32 v206, v210, v235
	ds_bpermute_b32 v207, v211, v235
	v_mov_b32_e32 v212, 0xbfb8aa3b
	v_mov_b32_e32 v214, 1.0
	v_mov_b64_e32 v[164:165], s[56:57]
	s_lshl_b32 s4, s5, 7
	s_ashr_i32 s5, s4, 31
	s_waitcnt lgkmcnt(0)
	v_fmamk_f32 v149, v200, 0x3a800000, v159
	v_rsq_f32_e32 v166, v149
	v_or_b32_e32 v149, s21, v153
	v_pk_mul_f32 v[124:125], v[124:125], v[166:167] op_sel_hi:[1,0]
	v_pk_mul_f32 v[128:129], v[128:129], v[166:167] op_sel_hi:[1,0]
	v_pk_mul_f32 v[126:127], v[126:127], v[166:167] op_sel_hi:[1,0]
	v_pk_mul_f32 v[122:123], v[122:123], v[166:167] op_sel_hi:[1,0]
	v_pk_mul_f32 v[120:121], v[120:121], v[166:167] op_sel_hi:[1,0]
	v_pk_mul_f32 v[118:119], v[118:119], v[166:167] op_sel_hi:[1,0]
	v_pk_mul_f32 v[116:117], v[116:117], v[166:167] op_sel_hi:[1,0]
	v_pk_mul_f32 v[114:115], v[114:115], v[166:167] op_sel_hi:[1,0]
	v_pk_mul_f32 v[216:217], v[122:123], v[212:213] op_sel_hi:[1,0]
	v_pk_mul_f32 v[218:219], v[124:125], v[212:213] op_sel_hi:[1,0]
	v_pk_mul_f32 v[220:221], v[126:127], v[212:213] op_sel_hi:[1,0]
	v_pk_mul_f32 v[222:223], v[128:129], v[212:213] op_sel_hi:[1,0]
	v_exp_f32_e32 v219, v219
	v_exp_f32_e32 v220, v220
	v_exp_f32_e32 v221, v221
	v_exp_f32_e32 v222, v222
	v_exp_f32_e32 v223, v223
	v_exp_f32_e32 v216, v216
	v_exp_f32_e32 v217, v217
	v_exp_f32_e32 v218, v218
	v_pk_add_f32 v[220:221], v[220:221], v[214:215] op_sel_hi:[1,0]
	v_pk_add_f32 v[222:223], v[222:223], v[214:215] op_sel_hi:[1,0]
	v_pk_add_f32 v[216:217], v[216:217], v[214:215] op_sel_hi:[1,0]
	v_pk_add_f32 v[218:219], v[218:219], v[214:215] op_sel_hi:[1,0]
	v_rcp_f32_e32 v219, v219
	v_rcp_f32_e32 v220, v220
	v_rcp_f32_e32 v221, v221
	v_rcp_f32_e32 v222, v222
	v_rcp_f32_e32 v223, v223
	v_rcp_f32_e32 v216, v216
	v_rcp_f32_e32 v217, v217
	v_rcp_f32_e32 v218, v218
	v_pk_mul_f32 v[126:127], v[126:127], v[220:221]
	v_pk_mul_f32 v[128:129], v[128:129], v[222:223]
	v_pk_mul_f32 v[122:123], v[122:123], v[216:217]
	v_pk_mul_f32 v[124:125], v[124:125], v[218:219]
	v_pk_mul_f32 v[122:123], v[114:115], v[122:123]
	v_pk_mul_f32 v[116:117], v[116:117], v[124:125]
	v_pk_mul_f32 v[118:119], v[118:119], v[126:127]
	v_pk_mul_f32 v[120:121], v[120:121], v[128:129]
	v_cvt_pk_bf16_f32 v114, v118, v119
	v_cvt_pk_bf16_f32 v115, v120, v121
	v_cvt_pk_bf16_f32 v117, v116, v117
	v_cvt_pk_bf16_f32 v116, v122, v123
	ds_write_b128 v160, v[114:117]
	ds_read_b128 v[116:119], v161
	v_mad_i64_i32 v[114:115], s[28:29], v149, s55, v[164:165]
	v_lshl_add_u64 v[114:115], s[4:5], 1, v[114:115]
	v_lshl_add_u64 v[114:115], v[114:115], 0, s[6:7]
	v_lshl_add_u64 v[114:115], v[114:115], 0, v[138:139]
	s_waitcnt lgkmcnt(0)
	global_store_dwordx4 v[114:115], v[116:119], off sc1
	s_nop 1
	v_fmamk_f32 v116, v201, 0x3a800000, v159
	v_rsq_f32_e32 v116, v116
	s_nop 0
	v_pk_mul_f32 v[108:109], v[108:109], v[116:117] op_sel_hi:[1,0]
	v_pk_mul_f32 v[112:113], v[112:113], v[116:117] op_sel_hi:[1,0]
	v_pk_mul_f32 v[110:111], v[110:111], v[116:117] op_sel_hi:[1,0]
	v_pk_mul_f32 v[106:107], v[106:107], v[116:117] op_sel_hi:[1,0]
	v_pk_mul_f32 v[104:105], v[104:105], v[116:117] op_sel_hi:[1,0]
	v_pk_mul_f32 v[102:103], v[102:103], v[116:117] op_sel_hi:[1,0]
	v_pk_mul_f32 v[100:101], v[100:101], v[116:117] op_sel_hi:[1,0]
	v_pk_mul_f32 v[98:99], v[98:99], v[116:117] op_sel_hi:[1,0]
	v_pk_mul_f32 v[216:217], v[106:107], v[212:213] op_sel_hi:[1,0]
	v_pk_mul_f32 v[218:219], v[108:109], v[212:213] op_sel_hi:[1,0]
	v_pk_mul_f32 v[220:221], v[110:111], v[212:213] op_sel_hi:[1,0]
	v_pk_mul_f32 v[222:223], v[112:113], v[212:213] op_sel_hi:[1,0]
	v_exp_f32_e32 v219, v219
	v_exp_f32_e32 v220, v220
	v_exp_f32_e32 v221, v221
	v_exp_f32_e32 v222, v222
	v_exp_f32_e32 v223, v223
	v_exp_f32_e32 v216, v216
	v_exp_f32_e32 v217, v217
	v_exp_f32_e32 v218, v218
	v_pk_add_f32 v[220:221], v[220:221], v[214:215] op_sel_hi:[1,0]
	v_pk_add_f32 v[222:223], v[222:223], v[214:215] op_sel_hi:[1,0]
	v_pk_add_f32 v[216:217], v[216:217], v[214:215] op_sel_hi:[1,0]
	v_pk_add_f32 v[218:219], v[218:219], v[214:215] op_sel_hi:[1,0]
	v_rcp_f32_e32 v219, v219
	v_rcp_f32_e32 v220, v220
	v_rcp_f32_e32 v221, v221
	v_rcp_f32_e32 v222, v222
	v_rcp_f32_e32 v223, v223
	v_rcp_f32_e32 v216, v216
	v_rcp_f32_e32 v217, v217
	v_rcp_f32_e32 v218, v218
	v_pk_mul_f32 v[110:111], v[110:111], v[220:221]
	v_pk_mul_f32 v[112:113], v[112:113], v[222:223]
	v_pk_mul_f32 v[106:107], v[106:107], v[216:217]
	v_pk_mul_f32 v[108:109], v[108:109], v[218:219]
	v_pk_mul_f32 v[106:107], v[98:99], v[106:107]
	v_pk_mul_f32 v[100:101], v[100:101], v[108:109]
	v_pk_mul_f32 v[102:103], v[102:103], v[110:111]
	v_pk_mul_f32 v[104:105], v[104:105], v[112:113]
	v_cvt_pk_bf16_f32 v98, v102, v103
	v_cvt_pk_bf16_f32 v99, v104, v105
	v_cvt_pk_bf16_f32 v101, v100, v101
	v_cvt_pk_bf16_f32 v100, v106, v107
	ds_write_b128 v162, v[98:101]
	ds_read_b128 v[98:101], v163
	v_add_co_u32_e32 v102, vcc, s41, v114
	s_nop 1
	v_addc_co_u32_e32 v103, vcc, 0, v115, vcc
	s_waitcnt lgkmcnt(0)
; __device__ __forceinline__ unsigned cvt_pk_bf16(float lo, float hi) { unsigned r; asm volatile("v_cvt_pk_bf16_f32 %0, %1, %2" : "=v"(r) : "v"(lo), "v"(hi)); return r; }
; #define LAS __attribute__((address_space(3)))
; __device__ __forceinline__ float siluf_(float x) { return x * __builtin_amdgcn_rcpf(1.0f + __builtin_amdgcn_exp2f(-1.4426950408889634f * x)); }
; __device__ __forceinline__ float rstd_of(float ss) { return __builtin_amdgcn_rsqf(ss * (1.0f / DM) + EPS); }
;     __device__ __forceinline__ void operator()(const pg8::f32x4 (&acc)[2][2][4][2], const Unit& u, int wr, int wc, int fr, int fq) const {
;         const int row0 = u.pm * BM + wr * 64, lane = fr + 16 * fq, rr = lane >> 2, sl = lane & 3;
;         LAS unsigned char* W = scr + (wr * 4 + wc) * 2048;
;         bf16* outp = ACT + (size_t)(row0 + rr) * DFF + u.pn * HALF + wc * 32 + sl * 8;
; #pragma unroll
;         for (int ai = 0; ai < 2; ++ai)
; #pragma unroll
;             for (int m = 0; m < 4; ++m) { const int rg = ai * HALF + m * 16; const float rs = rstd_of(SS1[row0 + rg + fr]);
;                 const pg8::f32x4 g0 = acc[ai][0][m][0] * rs, g1 = acc[ai][0][m][1] * rs, u0 = acc[ai][1][m][0] * rs, u1 = acc[ai][1][m][1] * rs;
;                 u32x4 w; w.x = cvt_pk_bf16(siluf_(g0[0]) * u0[0], siluf_(g0[1]) * u0[1]); w.y = cvt_pk_bf16(siluf_(g0[2]) * u0[2], siluf_(g0[3]) * u0[3]);
;                 w.z = cvt_pk_bf16(siluf_(g1[0]) * u1[0], siluf_(g1[1]) * u1[1]); w.w = cvt_pk_bf16(siluf_(g1[2]) * u1[2], siluf_(g1[3]) * u1[3]);
;                 *(LAS u32x4*)epi_slot(W, fr, fq + 4 * (m & 1)) = w;
;                 const u32x4 o = *(const LAS u32x4*)epi_slot(W, rr, sl + 4 * (m & 1));
;                 *(u32x4*)(outp + (size_t)rg * DFF) = o; }
	global_store_dwordx4 v[102:103], v[98:101], off sc1
	s_nop 1
	v_fmamk_f32 v98, v202, 0x3a800000, v159
	v_rsq_f32_e32 v98, v98
	s_nop 0
	v_pk_mul_f32 v[92:93], v[92:93], v[98:99] op_sel_hi:[1,0]
	v_pk_mul_f32 v[96:97], v[96:97], v[98:99] op_sel_hi:[1,0]
	v_pk_mul_f32 v[94:95], v[94:95], v[98:99] op_sel_hi:[1,0]
	v_pk_mul_f32 v[90:91], v[90:91], v[98:99] op_sel_hi:[1,0]
	v_pk_mul_f32 v[88:89], v[88:89], v[98:99] op_sel_hi:[1,0]
	v_pk_mul_f32 v[86:87], v[86:87], v[98:99] op_sel_hi:[1,0]
	v_pk_mul_f32 v[84:85], v[84:85], v[98:99] op_sel_hi:[1,0]
	v_pk_mul_f32 v[82:83], v[82:83], v[98:99] op_sel_hi:[1,0]
	v_pk_mul_f32 v[216:217], v[90:91], v[212:213] op_sel_hi:[1,0]
	v_pk_mul_f32 v[218:219], v[92:93], v[212:213] op_sel_hi:[1,0]
	v_pk_mul_f32 v[220:221], v[94:95], v[212:213] op_sel_hi:[1,0]
	v_pk_mul_f32 v[222:223], v[96:97], v[212:213] op_sel_hi:[1,0]
	v_exp_f32_e32 v219, v219
	v_exp_f32_e32 v220, v220
	v_exp_f32_e32 v221, v221
	v_exp_f32_e32 v222, v222
	v_exp_f32_e32 v223, v223
	v_exp_f32_e32 v216, v216
	v_exp_f32_e32 v217, v217
	v_exp_f32_e32 v218, v218
	v_pk_add_f32 v[220:221], v[220:221], v[214:215] op_sel_hi:[1,0]
	v_pk_add_f32 v[222:223], v[222:223], v[214:215] op_sel_hi:[1,0]
	v_pk_add_f32 v[216:217], v[216:217], v[214:215] op_sel_hi:[1,0]
	v_pk_add_f32 v[218:219], v[218:219], v[214:215] op_sel_hi:[1,0]
	v_rcp_f32_e32 v219, v219
	v_rcp_f32_e32 v220, v220
	v_rcp_f32_e32 v221, v221
	v_rcp_f32_e32 v222, v222
	v_rcp_f32_e32 v223, v223
	v_rcp_f32_e32 v216, v216
	v_rcp_f32_e32 v217, v217
	v_rcp_f32_e32 v218, v218
	v_pk_mul_f32 v[94:95], v[94:95], v[220:221]
	v_pk_mul_f32 v[96:97], v[96:97], v[222:223]
	v_pk_mul_f32 v[90:91], v[90:91], v[216:217]
	v_pk_mul_f32 v[92:93], v[92:93], v[218:219]
	v_pk_mul_f32 v[90:91], v[82:83], v[90:91]
	v_pk_mul_f32 v[84:85], v[84:85], v[92:93]
	v_pk_mul_f32 v[86:87], v[86:87], v[94:95]
	v_pk_mul_f32 v[88:89], v[88:89], v[96:97]
	v_cvt_pk_bf16_f32 v82, v86, v87
	v_cvt_pk_bf16_f32 v83, v88, v89
	v_cvt_pk_bf16_f32 v85, v84, v85
	v_cvt_pk_bf16_f32 v84, v90, v91
	ds_write_b128 v160, v[82:85]
	ds_read_b128 v[82:85], v161
	v_add_co_u32_e32 v86, vcc, s58, v114
	s_nop 1
	v_addc_co_u32_e32 v87, vcc, 0, v115, vcc
	s_waitcnt lgkmcnt(0)
	global_store_dwordx4 v[86:87], v[82:85], off sc1
	s_nop 1
	v_fmamk_f32 v82, v203, 0x3a800000, v159
	v_rsq_f32_e32 v82, v82
	s_nop 0
	v_pk_mul_f32 v[76:77], v[76:77], v[82:83] op_sel_hi:[1,0]
	v_pk_mul_f32 v[80:81], v[80:81], v[82:83] op_sel_hi:[1,0]
	v_pk_mul_f32 v[78:79], v[78:79], v[82:83] op_sel_hi:[1,0]
	v_pk_mul_f32 v[74:75], v[74:75], v[82:83] op_sel_hi:[1,0]
	v_pk_mul_f32 v[72:73], v[72:73], v[82:83] op_sel_hi:[1,0]
	v_pk_mul_f32 v[70:71], v[70:71], v[82:83] op_sel_hi:[1,0]
	v_pk_mul_f32 v[68:69], v[68:69], v[82:83] op_sel_hi:[1,0]
	v_pk_mul_f32 v[66:67], v[66:67], v[82:83] op_sel_hi:[1,0]
	v_pk_mul_f32 v[216:217], v[74:75], v[212:213] op_sel_hi:[1,0]
	v_pk_mul_f32 v[218:219], v[76:77], v[212:213] op_sel_hi:[1,0]
	v_pk_mul_f32 v[220:221], v[78:79], v[212:213] op_sel_hi:[1,0]
	v_pk_mul_f32 v[222:223], v[80:81], v[212:213] op_sel_hi:[1,0]
	v_exp_f32_e32 v219, v219
	v_exp_f32_e32 v220, v220
	v_exp_f32_e32 v221, v221
	v_exp_f32_e32 v222, v222
	v_exp_f32_e32 v223, v223
	v_exp_f32_e32 v216, v216
	v_exp_f32_e32 v217, v217
	v_exp_f32_e32 v218, v218
	v_pk_add_f32 v[220:221], v[220:221], v[214:215] op_sel_hi:[1,0]
	v_pk_add_f32 v[222:223], v[222:223], v[214:215] op_sel_hi:[1,0]
	v_pk_add_f32 v[216:217], v[216:217], v[214:215] op_sel_hi:[1,0]
	v_pk_add_f32 v[218:219], v[218:219], v[214:215] op_sel_hi:[1,0]
	v_rcp_f32_e32 v219, v219
	v_rcp_f32_e32 v220, v220
	v_rcp_f32_e32 v221, v221
	v_rcp_f32_e32 v222, v222
	v_rcp_f32_e32 v223, v223
	v_rcp_f32_e32 v216, v216
	v_rcp_f32_e32 v217, v217
	v_rcp_f32_e32 v218, v218
	v_pk_mul_f32 v[78:79], v[78:79], v[220:221]
	v_pk_mul_f32 v[80:81], v[80:81], v[222:223]
	v_pk_mul_f32 v[74:75], v[74:75], v[216:217]
	v_pk_mul_f32 v[76:77], v[76:77], v[218:219]
	v_pk_mul_f32 v[74:75], v[66:67], v[74:75]
	v_pk_mul_f32 v[68:69], v[68:69], v[76:77]
	v_pk_mul_f32 v[70:71], v[70:71], v[78:79]
	v_pk_mul_f32 v[72:73], v[72:73], v[80:81]
	v_cvt_pk_bf16_f32 v66, v70, v71
	v_cvt_pk_bf16_f32 v67, v72, v73
	v_cvt_pk_bf16_f32 v69, v68, v69
	v_cvt_pk_bf16_f32 v68, v74, v75
	ds_write_b128 v162, v[66:69]
	ds_read_b128 v[66:69], v163
	v_add_co_u32_e32 v70, vcc, s59, v114
	s_nop 1
	v_addc_co_u32_e32 v71, vcc, 0, v115, vcc
	s_waitcnt lgkmcnt(0)
	global_store_dwordx4 v[70:71], v[66:69], off sc1
	s_nop 1
	v_fmamk_f32 v66, v204, 0x3a800000, v159
	v_rsq_f32_e32 v66, v66
	s_nop 0
	v_pk_mul_f32 v[60:61], v[60:61], v[66:67] op_sel_hi:[1,0]
	v_pk_mul_f32 v[64:65], v[64:65], v[66:67] op_sel_hi:[1,0]
	v_pk_mul_f32 v[62:63], v[62:63], v[66:67] op_sel_hi:[1,0]
	v_pk_mul_f32 v[58:59], v[58:59], v[66:67] op_sel_hi:[1,0]
	v_pk_mul_f32 v[56:57], v[56:57], v[66:67] op_sel_hi:[1,0]
	v_pk_mul_f32 v[54:55], v[54:55], v[66:67] op_sel_hi:[1,0]
	v_pk_mul_f32 v[52:53], v[52:53], v[66:67] op_sel_hi:[1,0]
	v_pk_mul_f32 v[50:51], v[50:51], v[66:67] op_sel_hi:[1,0]
	v_pk_mul_f32 v[216:217], v[58:59], v[212:213] op_sel_hi:[1,0]
	v_pk_mul_f32 v[218:219], v[60:61], v[212:213] op_sel_hi:[1,0]
	v_pk_mul_f32 v[220:221], v[62:63], v[212:213] op_sel_hi:[1,0]
	v_pk_mul_f32 v[222:223], v[64:65], v[212:213] op_sel_hi:[1,0]
	v_exp_f32_e32 v219, v219
	v_exp_f32_e32 v220, v220
	v_exp_f32_e32 v221, v221
	v_exp_f32_e32 v222, v222
	v_exp_f32_e32 v223, v223
	v_exp_f32_e32 v216, v216
	v_exp_f32_e32 v217, v217
	v_exp_f32_e32 v218, v218
	v_pk_add_f32 v[220:221], v[220:221], v[214:215] op_sel_hi:[1,0]
	v_pk_add_f32 v[222:223], v[222:223], v[214:215] op_sel_hi:[1,0]
	v_pk_add_f32 v[216:217], v[216:217], v[214:215] op_sel_hi:[1,0]
	v_pk_add_f32 v[218:219], v[218:219], v[214:215] op_sel_hi:[1,0]
	v_rcp_f32_e32 v219, v219
	v_rcp_f32_e32 v220, v220
	v_rcp_f32_e32 v221, v221
	v_rcp_f32_e32 v222, v222
	v_rcp_f32_e32 v223, v223
	v_rcp_f32_e32 v216, v216
	v_rcp_f32_e32 v217, v217
	v_rcp_f32_e32 v218, v218
	v_pk_mul_f32 v[62:63], v[62:63], v[220:221]
	v_pk_mul_f32 v[64:65], v[64:65], v[222:223]
	v_pk_mul_f32 v[58:59], v[58:59], v[216:217]
	v_pk_mul_f32 v[60:61], v[60:61], v[218:219]
	v_pk_mul_f32 v[58:59], v[50:51], v[58:59]
	v_pk_mul_f32 v[52:53], v[52:53], v[60:61]
	v_pk_mul_f32 v[54:55], v[54:55], v[62:63]
	v_pk_mul_f32 v[56:57], v[56:57], v[64:65]
	v_cvt_pk_bf16_f32 v50, v54, v55
	v_cvt_pk_bf16_f32 v51, v56, v57
	v_cvt_pk_bf16_f32 v53, v52, v53
	v_cvt_pk_bf16_f32 v52, v58, v59
	ds_write_b128 v160, v[50:53]
	ds_read_b128 v[50:53], v161
	v_add_co_u32_e32 v54, vcc, s60, v114
	s_nop 1
	v_addc_co_u32_e32 v55, vcc, 0, v115, vcc
	s_waitcnt lgkmcnt(0)
; __device__ __forceinline__ unsigned cvt_pk_bf16(float lo, float hi) { unsigned r; asm volatile("v_cvt_pk_bf16_f32 %0, %1, %2" : "=v"(r) : "v"(lo), "v"(hi)); return r; }
; #define LAS __attribute__((address_space(3)))
; __device__ __forceinline__ float siluf_(float x) { return x * __builtin_amdgcn_rcpf(1.0f + __builtin_amdgcn_exp2f(-1.4426950408889634f * x)); }
; __device__ __forceinline__ float rstd_of(float ss) { return __builtin_amdgcn_rsqf(ss * (1.0f / DM) + EPS); }
;     __device__ __forceinline__ void operator()(const pg8::f32x4 (&acc)[2][2][4][2], const Unit& u, int wr, int wc, int fr, int fq) const {
;         const int row0 = u.pm * BM + wr * 64, lane = fr + 16 * fq, rr = lane >> 2, sl = lane & 3;
;         LAS unsigned char* W = scr + (wr * 4 + wc) * 2048;
;         bf16* outp = ACT + (size_t)(row0 + rr) * DFF + u.pn * HALF + wc * 32 + sl * 8;
; #pragma unroll
;         for (int ai = 0; ai < 2; ++ai)
; #pragma unroll
;             for (int m = 0; m < 4; ++m) { const int rg = ai * HALF + m * 16; const float rs = rstd_of(SS1[row0 + rg + fr]);
;                 const pg8::f32x4 g0 = acc[ai][0][m][0] * rs, g1 = acc[ai][0][m][1] * rs, u0 = acc[ai][1][m][0] * rs, u1 = acc[ai][1][m][1] * rs;
;                 u32x4 w; w.x = cvt_pk_bf16(siluf_(g0[0]) * u0[0], siluf_(g0[1]) * u0[1]); w.y = cvt_pk_bf16(siluf_(g0[2]) * u0[2], siluf_(g0[3]) * u0[3]);
;                 w.z = cvt_pk_bf16(siluf_(g1[0]) * u1[0], siluf_(g1[1]) * u1[1]); w.w = cvt_pk_bf16(siluf_(g1[2]) * u1[2], siluf_(g1[3]) * u1[3]);
;                 *(LAS u32x4*)epi_slot(W, fr, fq + 4 * (m & 1)) = w;
;                 const u32x4 o = *(const LAS u32x4*)epi_slot(W, rr, sl + 4 * (m & 1));
;                 *(u32x4*)(outp + (size_t)rg * DFF) = o; }
	global_store_dwordx4 v[54:55], v[50:53], off sc1
	s_nop 1
	v_fmamk_f32 v50, v205, 0x3a800000, v159
	v_rsq_f32_e32 v50, v50
	s_nop 0
	v_pk_mul_f32 v[44:45], v[44:45], v[50:51] op_sel_hi:[1,0]
	v_pk_mul_f32 v[48:49], v[48:49], v[50:51] op_sel_hi:[1,0]
	v_pk_mul_f32 v[46:47], v[46:47], v[50:51] op_sel_hi:[1,0]
	v_pk_mul_f32 v[42:43], v[42:43], v[50:51] op_sel_hi:[1,0]
	v_pk_mul_f32 v[40:41], v[40:41], v[50:51] op_sel_hi:[1,0]
	v_pk_mul_f32 v[38:39], v[38:39], v[50:51] op_sel_hi:[1,0]
	v_pk_mul_f32 v[36:37], v[36:37], v[50:51] op_sel_hi:[1,0]
	v_pk_mul_f32 v[34:35], v[34:35], v[50:51] op_sel_hi:[1,0]
	v_pk_mul_f32 v[216:217], v[42:43], v[212:213] op_sel_hi:[1,0]
	v_pk_mul_f32 v[218:219], v[44:45], v[212:213] op_sel_hi:[1,0]
	v_pk_mul_f32 v[220:221], v[46:47], v[212:213] op_sel_hi:[1,0]
	v_pk_mul_f32 v[222:223], v[48:49], v[212:213] op_sel_hi:[1,0]
	v_exp_f32_e32 v219, v219
	v_exp_f32_e32 v220, v220
	v_exp_f32_e32 v221, v221
	v_exp_f32_e32 v222, v222
	v_exp_f32_e32 v223, v223
	v_exp_f32_e32 v216, v216
	v_exp_f32_e32 v217, v217
	v_exp_f32_e32 v218, v218
	v_pk_add_f32 v[220:221], v[220:221], v[214:215] op_sel_hi:[1,0]
	v_pk_add_f32 v[222:223], v[222:223], v[214:215] op_sel_hi:[1,0]
	v_pk_add_f32 v[216:217], v[216:217], v[214:215] op_sel_hi:[1,0]
	v_pk_add_f32 v[218:219], v[218:219], v[214:215] op_sel_hi:[1,0]
	v_rcp_f32_e32 v219, v219
	v_rcp_f32_e32 v220, v220
	v_rcp_f32_e32 v221, v221
	v_rcp_f32_e32 v222, v222
	v_rcp_f32_e32 v223, v223
	v_rcp_f32_e32 v216, v216
	v_rcp_f32_e32 v217, v217
	v_rcp_f32_e32 v218, v218
	v_pk_mul_f32 v[46:47], v[46:47], v[220:221]
	v_pk_mul_f32 v[48:49], v[48:49], v[222:223]
	v_pk_mul_f32 v[42:43], v[42:43], v[216:217]
	v_pk_mul_f32 v[44:45], v[44:45], v[218:219]
	v_pk_mul_f32 v[42:43], v[34:35], v[42:43]
	v_pk_mul_f32 v[36:37], v[36:37], v[44:45]
	v_pk_mul_f32 v[38:39], v[38:39], v[46:47]
	v_pk_mul_f32 v[40:41], v[40:41], v[48:49]
	v_cvt_pk_bf16_f32 v34, v38, v39
	v_cvt_pk_bf16_f32 v35, v40, v41
	v_cvt_pk_bf16_f32 v37, v36, v37
	v_cvt_pk_bf16_f32 v36, v42, v43
	ds_write_b128 v162, v[34:37]
	ds_read_b128 v[34:37], v163
	v_add_co_u32_e32 v38, vcc, s61, v114
	s_nop 1
	v_addc_co_u32_e32 v39, vcc, 0, v115, vcc
	s_waitcnt lgkmcnt(0)
	global_store_dwordx4 v[38:39], v[34:37], off sc1
	s_nop 1
	v_fmamk_f32 v34, v206, 0x3a800000, v159
	v_rsq_f32_e32 v34, v34
	s_nop 0
	v_pk_mul_f32 v[28:29], v[28:29], v[34:35] op_sel_hi:[1,0]
	v_pk_mul_f32 v[32:33], v[32:33], v[34:35] op_sel_hi:[1,0]
	v_pk_mul_f32 v[30:31], v[30:31], v[34:35] op_sel_hi:[1,0]
	v_pk_mul_f32 v[26:27], v[26:27], v[34:35] op_sel_hi:[1,0]
	v_pk_mul_f32 v[24:25], v[24:25], v[34:35] op_sel_hi:[1,0]
	v_pk_mul_f32 v[22:23], v[22:23], v[34:35] op_sel_hi:[1,0]
	v_pk_mul_f32 v[20:21], v[20:21], v[34:35] op_sel_hi:[1,0]
	v_pk_mul_f32 v[18:19], v[18:19], v[34:35] op_sel_hi:[1,0]
	v_pk_mul_f32 v[216:217], v[26:27], v[212:213] op_sel_hi:[1,0]
	v_pk_mul_f32 v[218:219], v[28:29], v[212:213] op_sel_hi:[1,0]
	v_pk_mul_f32 v[220:221], v[30:31], v[212:213] op_sel_hi:[1,0]
	v_pk_mul_f32 v[222:223], v[32:33], v[212:213] op_sel_hi:[1,0]
	v_exp_f32_e32 v219, v219
	v_exp_f32_e32 v220, v220
	v_exp_f32_e32 v221, v221
	v_exp_f32_e32 v222, v222
	v_exp_f32_e32 v223, v223
	v_exp_f32_e32 v216, v216
	v_exp_f32_e32 v217, v217
	v_exp_f32_e32 v218, v218
	v_pk_add_f32 v[220:221], v[220:221], v[214:215] op_sel_hi:[1,0]
	v_pk_add_f32 v[222:223], v[222:223], v[214:215] op_sel_hi:[1,0]
	v_pk_add_f32 v[216:217], v[216:217], v[214:215] op_sel_hi:[1,0]
	v_pk_add_f32 v[218:219], v[218:219], v[214:215] op_sel_hi:[1,0]
	v_rcp_f32_e32 v219, v219
	v_rcp_f32_e32 v220, v220
	v_rcp_f32_e32 v221, v221
	v_rcp_f32_e32 v222, v222
	v_rcp_f32_e32 v223, v223
	v_rcp_f32_e32 v216, v216
	v_rcp_f32_e32 v217, v217
	v_rcp_f32_e32 v218, v218
	v_pk_mul_f32 v[30:31], v[30:31], v[220:221]
	v_pk_mul_f32 v[32:33], v[32:33], v[222:223]
	v_pk_mul_f32 v[26:27], v[26:27], v[216:217]
	v_pk_mul_f32 v[28:29], v[28:29], v[218:219]
	v_pk_mul_f32 v[26:27], v[18:19], v[26:27]
	v_pk_mul_f32 v[20:21], v[20:21], v[28:29]
	v_pk_mul_f32 v[22:23], v[22:23], v[30:31]
	v_pk_mul_f32 v[24:25], v[24:25], v[32:33]
	v_cvt_pk_bf16_f32 v18, v22, v23
	v_cvt_pk_bf16_f32 v19, v24, v25
	v_cvt_pk_bf16_f32 v21, v20, v21
	v_cvt_pk_bf16_f32 v20, v26, v27
	ds_write_b128 v160, v[18:21]
	ds_read_b128 v[18:21], v161
	v_add_co_u32_e32 v22, vcc, s62, v114
	s_nop 1
	v_addc_co_u32_e32 v23, vcc, 0, v115, vcc
	s_waitcnt lgkmcnt(0)
	global_store_dwordx4 v[22:23], v[18:21], off sc1
	s_nop 1
	v_add_co_u32_e32 v20, vcc, 0xf2000, v114
	v_fmamk_f32 v18, v207, 0x3a800000, v159
	v_rsq_f32_e32 v18, v18
	s_nop 0
	v_pk_mul_f32 v[12:13], v[12:13], v[18:19] op_sel_hi:[1,0]
	v_pk_mul_f32 v[16:17], v[16:17], v[18:19] op_sel_hi:[1,0]
	v_pk_mul_f32 v[14:15], v[14:15], v[18:19] op_sel_hi:[1,0]
	v_pk_mul_f32 v[10:11], v[10:11], v[18:19] op_sel_hi:[1,0]
	v_pk_mul_f32 v[8:9], v[8:9], v[18:19] op_sel_hi:[1,0]
	v_pk_mul_f32 v[6:7], v[6:7], v[18:19] op_sel_hi:[1,0]
	v_pk_mul_f32 v[4:5], v[4:5], v[18:19] op_sel_hi:[1,0]
	v_pk_mul_f32 v[2:3], v[2:3], v[18:19] op_sel_hi:[1,0]
	v_pk_mul_f32 v[216:217], v[10:11], v[212:213] op_sel_hi:[1,0]
	v_pk_mul_f32 v[218:219], v[12:13], v[212:213] op_sel_hi:[1,0]
	v_pk_mul_f32 v[220:221], v[14:15], v[212:213] op_sel_hi:[1,0]
	v_pk_mul_f32 v[222:223], v[16:17], v[212:213] op_sel_hi:[1,0]
	v_exp_f32_e32 v219, v219
	v_exp_f32_e32 v220, v220
	v_exp_f32_e32 v221, v221
	v_exp_f32_e32 v222, v222
	v_exp_f32_e32 v223, v223
	v_exp_f32_e32 v216, v216
	v_exp_f32_e32 v217, v217
	v_exp_f32_e32 v218, v218
	v_pk_add_f32 v[220:221], v[220:221], v[214:215] op_sel_hi:[1,0]
	v_pk_add_f32 v[222:223], v[222:223], v[214:215] op_sel_hi:[1,0]
	v_pk_add_f32 v[216:217], v[216:217], v[214:215] op_sel_hi:[1,0]
	v_pk_add_f32 v[218:219], v[218:219], v[214:215] op_sel_hi:[1,0]
	v_rcp_f32_e32 v219, v219
	v_rcp_f32_e32 v220, v220
	v_rcp_f32_e32 v221, v221
	v_rcp_f32_e32 v222, v222
	v_rcp_f32_e32 v223, v223
	v_rcp_f32_e32 v216, v216
	v_rcp_f32_e32 v217, v217
	v_rcp_f32_e32 v218, v218
	v_pk_mul_f32 v[14:15], v[14:15], v[220:221]
	v_pk_mul_f32 v[16:17], v[16:17], v[222:223]
	v_pk_mul_f32 v[10:11], v[10:11], v[216:217]
	v_pk_mul_f32 v[12:13], v[12:13], v[218:219]
	v_pk_mul_f32 v[10:11], v[2:3], v[10:11]
	v_pk_mul_f32 v[4:5], v[4:5], v[12:13]
	v_pk_mul_f32 v[6:7], v[6:7], v[14:15]
	v_pk_mul_f32 v[8:9], v[8:9], v[16:17]
	v_cvt_pk_bf16_f32 v2, v6, v7
	v_cvt_pk_bf16_f32 v3, v8, v9
	v_cvt_pk_bf16_f32 v5, v4, v5
	v_cvt_pk_bf16_f32 v4, v10, v11
	ds_write_b128 v162, v[2:5]
	ds_read_b128 v[2:5], v163
	v_addc_co_u32_e32 v21, vcc, 0, v115, vcc
	s_andn2_b64 vcc, exec, s[0:1]
	s_mov_b64 s[0:1], -1
	s_waitcnt lgkmcnt(0)
	global_store_dwordx4 v[20:21], v[2:5], off sc1
	s_cbranch_vccnz .LBB0_873
	s_andn2_b64 vcc, exec, s[12:13]
	s_cbranch_vccnz .LBB0_872
	s_barrier
	s_branch .LBB0_872
